# v25
# speedup vs baseline: 1.0047x; 1.0047x over previous
; DI int crow(int reg, int h) { return (reg & 3) + 8 * (reg >> 2) + 4 * h; }
; #define MFMA32(a, b, c) __builtin_amdgcn_mfma_f32_32x32x16_bf16((a), (b), (c), 0, 0, 0)
; DI void mla_item(const Params& p, int b, int h, int qb) {
;     ...
;     if (kt < wkt) {
;       f32x16 sa[NSUB];
;       #pragma unroll
;       for (int sub = 0; sub < NSUB; ++sub) {
;         for (int i = 0; i < 16; ++i) sa[sub][i] = 0.f;
;         #pragma unroll
;         for (int s = 0; s < 6; ++s) {
;           bf16x8 a0 = *(const bf16x8*)(kb + ((sub * 32 + r) * KSTR + 16 * s + 8 * hh) * 2);
;           sa[sub] = MFMA32(a0, qf[s], sa[sub]);
;         }
;       }
;       if (kt * KT + KT - 1 > wq0) {
;         #pragma unroll
;         for (int sub = 0; sub < NSUB; ++sub)
;           for (int i = 0; i < 16; ++i) { int key = kt * KT + sub * 32 + crow(i, hh); if (key > qi) sa[sub][i] = -1e30f; }
.LBB0_913:
	s_and_b32 s37, s24, 1
	s_mul_i32 s24, s37, 0x6800
	v_add_u32_e32 v0, s24, v202
	ds_read_b128 v[212:215], v0
	ds_read_b128 v[216:219], v0 offset:32
	ds_read_b128 v[220:223], v0 offset:64
	ds_read_b128 v[224:227], v0 offset:96
	ds_read_b128 v[228:231], v0 offset:128
	ds_read_b128 v[232:235], v0 offset:160
	ds_read_b128 v[236:239], v0 offset:6656
	ds_read_b128 v[240:243], v0 offset:6688
	s_add_i32 s24, s35, 0x7f
	v_cmp_gt_i32_e32 vcc, s24, v167
	s_waitcnt lgkmcnt(7)
	v_mfma_f32_32x32x16_bf16 v[82:97], v[212:215], v[102:105], 0
	ds_read_b128 v[212:215], v0 offset:6720
	s_waitcnt lgkmcnt(7)
	v_mfma_f32_32x32x16_bf16 v[82:97], v[216:219], v[98:101], v[82:97]
	ds_read_b128 v[216:219], v0 offset:6752
	s_waitcnt lgkmcnt(7)
	v_mfma_f32_32x32x16_bf16 v[82:97], v[220:223], v[110:113], v[82:97]
	ds_read_b128 v[220:223], v0 offset:6784
	s_waitcnt lgkmcnt(7)
	v_mfma_f32_32x32x16_bf16 v[82:97], v[224:227], v[106:109], v[82:97]
	ds_read_b128 v[224:227], v0 offset:6816
	s_waitcnt lgkmcnt(7)
	v_mfma_f32_32x32x16_bf16 v[82:97], v[228:231], v[118:121], v[82:97]
	ds_read_b128 v[228:231], v0 offset:13312
	s_waitcnt lgkmcnt(7)
	v_mfma_f32_32x32x16_bf16 v[82:97], v[232:235], v[114:117], v[82:97]
	ds_read_b128 v[232:235], v0 offset:13344
	s_waitcnt lgkmcnt(7)
	v_mfma_f32_32x32x16_bf16 v[66:81], v[236:239], v[102:105], 0
	ds_read_b128 v[236:239], v0 offset:13376
	s_waitcnt lgkmcnt(7)
	v_mfma_f32_32x32x16_bf16 v[66:81], v[240:243], v[98:101], v[66:81]
	ds_read_b128 v[240:243], v0 offset:13408
	s_waitcnt lgkmcnt(7)
	v_mfma_f32_32x32x16_bf16 v[66:81], v[212:215], v[110:113], v[66:81]
	ds_read_b128 v[212:215], v0 offset:13440
	s_waitcnt lgkmcnt(7)
	v_mfma_f32_32x32x16_bf16 v[66:81], v[216:219], v[106:109], v[66:81]
	ds_read_b128 v[216:219], v0 offset:13472
	s_waitcnt lgkmcnt(7)
	v_mfma_f32_32x32x16_bf16 v[66:81], v[220:223], v[118:121], v[66:81]
	ds_read_b128 v[220:223], v0 offset:19968
	s_waitcnt lgkmcnt(7)
	v_mfma_f32_32x32x16_bf16 v[66:81], v[224:227], v[114:117], v[66:81]
	ds_read_b128 v[224:227], v0 offset:20000
	s_waitcnt lgkmcnt(7)
	v_mfma_f32_32x32x16_bf16 v[50:65], v[228:231], v[102:105], 0
	ds_read_b128 v[228:231], v0 offset:20032
	s_waitcnt lgkmcnt(7)
	v_mfma_f32_32x32x16_bf16 v[50:65], v[232:235], v[98:101], v[50:65]
	ds_read_b128 v[232:235], v0 offset:20064
	s_waitcnt lgkmcnt(7)
	v_mfma_f32_32x32x16_bf16 v[50:65], v[236:239], v[110:113], v[50:65]
	ds_read_b128 v[236:239], v0 offset:20096
	s_waitcnt lgkmcnt(7)
	v_mfma_f32_32x32x16_bf16 v[50:65], v[240:243], v[106:109], v[50:65]
	ds_read_b128 v[240:243], v0 offset:20128
	s_waitcnt lgkmcnt(7)
	v_mfma_f32_32x32x16_bf16 v[50:65], v[212:215], v[118:121], v[50:65]
	s_waitcnt lgkmcnt(6)
	v_mfma_f32_32x32x16_bf16 v[50:65], v[216:219], v[114:117], v[50:65]
	s_waitcnt lgkmcnt(5)
	v_mfma_f32_32x32x16_bf16 v[34:49], v[220:223], v[102:105], 0
	s_waitcnt lgkmcnt(4)
	v_mfma_f32_32x32x16_bf16 v[34:49], v[224:227], v[98:101], v[34:49]
	s_waitcnt lgkmcnt(3)
	v_mfma_f32_32x32x16_bf16 v[34:49], v[228:231], v[110:113], v[34:49]
	s_waitcnt lgkmcnt(2)
	v_mfma_f32_32x32x16_bf16 v[34:49], v[232:235], v[106:109], v[34:49]
	s_waitcnt lgkmcnt(1)
	v_mfma_f32_32x32x16_bf16 v[34:49], v[236:239], v[118:121], v[34:49]
	s_waitcnt lgkmcnt(0)
	v_mfma_f32_32x32x16_bf16 v[34:49], v[240:243], v[114:117], v[34:49]
	s_and_saveexec_b64 s[24:25], vcc
	s_cbranch_execz .LBB0_915
	v_add_u32_e32 v0, s35, v176
	v_cmp_lt_i32_e32 vcc, v0, v142
	v_add_u32_e32 v182, 2, v0
	s_nop 0
	v_cndmask_b32_e32 v83, v185, v83, vcc
	v_cmp_le_i32_e32 vcc, v0, v142
	s_nop 1
	v_cndmask_b32_e32 v82, v185, v82, vcc
	v_cmp_le_i32_e32 vcc, v182, v142
	v_add_u32_e32 v182, 3, v0
	s_nop 0
	v_cndmask_b32_e32 v84, v185, v84, vcc
	v_cmp_le_i32_e32 vcc, v182, v142
	v_add_u32_e32 v182, 8, v0
	s_nop 0
	v_cndmask_b32_e32 v85, v185, v85, vcc
	v_cmp_le_i32_e32 vcc, v182, v142
	v_add_u32_e32 v182, 9, v0
	s_nop 0
	v_cndmask_b32_e32 v86, v185, v86, vcc
	v_cmp_le_i32_e32 vcc, v182, v142
	v_add_u32_e32 v182, 10, v0
	s_nop 0
	v_cndmask_b32_e32 v87, v185, v87, vcc
	v_cmp_le_i32_e32 vcc, v182, v142
	v_add_u32_e32 v182, 11, v0
	s_nop 0
	v_cndmask_b32_e32 v88, v185, v88, vcc
	v_cmp_le_i32_e32 vcc, v182, v142
	v_add_u32_e32 v182, 16, v0
	s_nop 0
	v_cndmask_b32_e32 v89, v185, v89, vcc
	v_cmp_le_i32_e32 vcc, v182, v142
	v_add_u32_e32 v182, 17, v0
	s_nop 0
	v_cndmask_b32_e32 v90, v185, v90, vcc
	v_cmp_le_i32_e32 vcc, v182, v142
	v_add_u32_e32 v182, 18, v0
	s_nop 0
	v_cndmask_b32_e32 v91, v185, v91, vcc
	v_cmp_le_i32_e32 vcc, v182, v142
	v_add_u32_e32 v182, 19, v0
	s_nop 0
	v_cndmask_b32_e32 v92, v185, v92, vcc
	v_cmp_le_i32_e32 vcc, v182, v142
	v_add_u32_e32 v182, 24, v0
	s_nop 0
	v_cndmask_b32_e32 v93, v185, v93, vcc
	v_cmp_le_i32_e32 vcc, v182, v142
	v_add_u32_e32 v182, 25, v0
	s_nop 0
	v_cndmask_b32_e32 v94, v185, v94, vcc
	v_cmp_le_i32_e32 vcc, v182, v142
	v_add_u32_e32 v182, 26, v0
	s_nop 0
	v_cndmask_b32_e32 v95, v185, v95, vcc
	v_cmp_le_i32_e32 vcc, v182, v142
	v_add_u32_e32 v182, 27, v0
	s_nop 0
	v_cndmask_b32_e32 v96, v185, v96, vcc
	v_cmp_le_i32_e32 vcc, v182, v142
	v_add_u32_e32 v182, 32, v0
	s_nop 0
	v_cndmask_b32_e32 v97, v185, v97, vcc
	v_cmp_le_i32_e32 vcc, v182, v142
	v_add_u32_e32 v182, 33, v0
	s_nop 0
	v_cndmask_b32_e32 v66, v185, v66, vcc
; DI int crow(int reg, int h) { return (reg & 3) + 8 * (reg >> 2) + 4 * h; }
; DI void mla_item(const Params& p, int b, int h, int qb) {
;     ...
;       if (kt * KT + KT - 1 > wq0) {
;         #pragma unroll
;         for (int sub = 0; sub < NSUB; ++sub)
;           for (int i = 0; i < 16; ++i) { int key = kt * KT + sub * 32 + crow(i, hh); if (key > qi) sa[sub][i] = -1e30f; }
	v_cmp_le_i32_e32 vcc, v182, v142
	v_add_u32_e32 v182, 34, v0
	s_nop 0
	v_cndmask_b32_e32 v67, v185, v67, vcc
	v_cmp_le_i32_e32 vcc, v182, v142
	v_add_u32_e32 v182, 35, v0
	s_nop 0
	v_cndmask_b32_e32 v68, v185, v68, vcc
	v_cmp_le_i32_e32 vcc, v182, v142
	v_add_u32_e32 v182, 40, v0
	s_nop 0
	v_cndmask_b32_e32 v69, v185, v69, vcc
	v_cmp_le_i32_e32 vcc, v182, v142
	v_add_u32_e32 v182, 41, v0
	s_nop 0
	v_cndmask_b32_e32 v70, v185, v70, vcc
	v_cmp_le_i32_e32 vcc, v182, v142
	v_add_u32_e32 v182, 42, v0
	s_nop 0
	v_cndmask_b32_e32 v71, v185, v71, vcc
	v_cmp_le_i32_e32 vcc, v182, v142
	v_add_u32_e32 v182, 43, v0
	s_nop 0
	v_cndmask_b32_e32 v72, v185, v72, vcc
	v_cmp_le_i32_e32 vcc, v182, v142
	v_add_u32_e32 v182, 48, v0
	s_nop 0
	v_cndmask_b32_e32 v73, v185, v73, vcc
	v_cmp_le_i32_e32 vcc, v182, v142
	v_add_u32_e32 v182, 49, v0
	s_nop 0
	v_cndmask_b32_e32 v74, v185, v74, vcc
	v_cmp_le_i32_e32 vcc, v182, v142
	v_add_u32_e32 v182, 50, v0
	s_nop 0
	v_cndmask_b32_e32 v75, v185, v75, vcc
	v_cmp_le_i32_e32 vcc, v182, v142
	v_add_u32_e32 v182, 51, v0
	s_nop 0
	v_cndmask_b32_e32 v76, v185, v76, vcc
	v_cmp_le_i32_e32 vcc, v182, v142
	v_add_u32_e32 v182, 56, v0
	s_nop 0
	v_cndmask_b32_e32 v77, v185, v77, vcc
	v_cmp_le_i32_e32 vcc, v182, v142
	v_add_u32_e32 v182, 57, v0
	s_nop 0
	v_cndmask_b32_e32 v78, v185, v78, vcc
	v_cmp_le_i32_e32 vcc, v182, v142
	v_add_u32_e32 v182, 58, v0
	s_nop 0
	v_cndmask_b32_e32 v79, v185, v79, vcc
	v_cmp_le_i32_e32 vcc, v182, v142
	v_add_u32_e32 v182, 59, v0
	s_nop 0
	v_cndmask_b32_e32 v80, v185, v80, vcc
	v_cmp_le_i32_e32 vcc, v182, v142
	v_add_u32_e32 v182, 64, v0
	s_nop 0
	v_cndmask_b32_e32 v81, v185, v81, vcc
	v_cmp_le_i32_e32 vcc, v182, v142
	v_add_u32_e32 v182, 0x41, v0
	s_nop 0
	v_cndmask_b32_e32 v50, v185, v50, vcc
	v_cmp_le_i32_e32 vcc, v182, v142
	v_add_u32_e32 v182, 0x42, v0
	s_nop 0
	v_cndmask_b32_e32 v51, v185, v51, vcc
	v_cmp_le_i32_e32 vcc, v182, v142
	v_add_u32_e32 v182, 0x43, v0
	s_nop 0
	v_cndmask_b32_e32 v52, v185, v52, vcc
	v_cmp_le_i32_e32 vcc, v182, v142
	v_add_u32_e32 v182, 0x48, v0
	s_nop 0
	v_cndmask_b32_e32 v53, v185, v53, vcc
	v_cmp_le_i32_e32 vcc, v182, v142
	v_add_u32_e32 v182, 0x49, v0
	s_nop 0
	v_cndmask_b32_e32 v54, v185, v54, vcc
	v_cmp_le_i32_e32 vcc, v182, v142
	v_add_u32_e32 v182, 0x4a, v0
	s_nop 0
	v_cndmask_b32_e32 v55, v185, v55, vcc
	v_cmp_le_i32_e32 vcc, v182, v142
	v_add_u32_e32 v182, 0x4b, v0
	s_nop 0
	v_cndmask_b32_e32 v56, v185, v56, vcc
	v_cmp_le_i32_e32 vcc, v182, v142
	v_add_u32_e32 v182, 0x50, v0
	s_nop 0
	v_cndmask_b32_e32 v57, v185, v57, vcc
	v_cmp_le_i32_e32 vcc, v182, v142
	v_add_u32_e32 v182, 0x51, v0
	s_nop 0
	v_cndmask_b32_e32 v58, v185, v58, vcc
	v_cmp_le_i32_e32 vcc, v182, v142
	v_add_u32_e32 v182, 0x52, v0
	s_nop 0
	v_cndmask_b32_e32 v59, v185, v59, vcc
	v_cmp_le_i32_e32 vcc, v182, v142
	v_add_u32_e32 v182, 0x53, v0
	s_nop 0
	v_cndmask_b32_e32 v60, v185, v60, vcc
	v_cmp_le_i32_e32 vcc, v182, v142
	v_add_u32_e32 v182, 0x58, v0
	s_nop 0
	v_cndmask_b32_e32 v61, v185, v61, vcc
	v_cmp_le_i32_e32 vcc, v182, v142
	v_add_u32_e32 v182, 0x59, v0
	s_nop 0
	v_cndmask_b32_e32 v62, v185, v62, vcc
	v_cmp_le_i32_e32 vcc, v182, v142
	v_add_u32_e32 v182, 0x5a, v0
	s_nop 0
	v_cndmask_b32_e32 v63, v185, v63, vcc
	v_cmp_le_i32_e32 vcc, v182, v142
	v_add_u32_e32 v182, 0x5b, v0
	s_nop 0
	v_cndmask_b32_e32 v64, v185, v64, vcc
	v_cmp_le_i32_e32 vcc, v182, v142
	v_add_u32_e32 v182, 0x60, v0
	s_nop 0
	v_cndmask_b32_e32 v65, v185, v65, vcc
	v_cmp_le_i32_e32 vcc, v182, v142
	v_add_u32_e32 v182, 0x61, v0
	s_nop 0
	v_cndmask_b32_e32 v34, v185, v34, vcc
	v_cmp_le_i32_e32 vcc, v182, v142
	v_add_u32_e32 v182, 0x62, v0
	s_nop 0
	v_cndmask_b32_e32 v35, v185, v35, vcc
	v_cmp_le_i32_e32 vcc, v182, v142
	v_add_u32_e32 v182, 0x63, v0
	s_nop 0
	v_cndmask_b32_e32 v36, v185, v36, vcc
	v_cmp_le_i32_e32 vcc, v182, v142
	v_add_u32_e32 v182, 0x68, v0
	s_nop 0
	v_cndmask_b32_e32 v37, v185, v37, vcc
	v_cmp_le_i32_e32 vcc, v182, v142
	v_add_u32_e32 v182, 0x69, v0
	s_nop 0
	v_cndmask_b32_e32 v38, v185, v38, vcc
	v_cmp_le_i32_e32 vcc, v182, v142
	v_add_u32_e32 v182, 0x6a, v0
	s_nop 0
	v_cndmask_b32_e32 v39, v185, v39, vcc
	v_cmp_le_i32_e32 vcc, v182, v142
	v_add_u32_e32 v182, 0x6b, v0
	s_nop 0
	v_cndmask_b32_e32 v40, v185, v40, vcc
	v_cmp_le_i32_e32 vcc, v182, v142
	v_add_u32_e32 v182, 0x70, v0
	s_nop 0
	v_cndmask_b32_e32 v41, v185, v41, vcc
	v_cmp_le_i32_e32 vcc, v182, v142
	v_add_u32_e32 v182, 0x71, v0
	s_nop 0
	v_cndmask_b32_e32 v42, v185, v42, vcc
	v_cmp_le_i32_e32 vcc, v182, v142
	v_add_u32_e32 v182, 0x72, v0
	s_nop 0
	v_cndmask_b32_e32 v43, v185, v43, vcc
	v_cmp_le_i32_e32 vcc, v182, v142
	v_add_u32_e32 v182, 0x73, v0
	s_nop 0
	v_cndmask_b32_e32 v44, v185, v44, vcc
	v_cmp_le_i32_e32 vcc, v182, v142
	v_add_u32_e32 v182, 0x78, v0
	s_nop 0
	v_cndmask_b32_e32 v45, v185, v45, vcc
	v_cmp_le_i32_e32 vcc, v182, v142
	v_add_u32_e32 v182, 0x79, v0
	s_nop 0
	v_cndmask_b32_e32 v46, v185, v46, vcc
	v_cmp_le_i32_e32 vcc, v182, v142
	v_add_u32_e32 v182, 0x7a, v0
	v_add_u32_e32 v0, 0x7b, v0
	v_cndmask_b32_e32 v47, v185, v47, vcc
	v_cmp_le_i32_e32 vcc, v182, v142
	s_nop 1
	v_cndmask_b32_e32 v48, v185, v48, vcc
	v_cmp_le_i32_e32 vcc, v0, v142
	s_nop 1
	v_cndmask_b32_e32 v49, v185, v49, vcc
